# out-projection epilogue: once-read residual x rows loaded with the nt (streaming) policy
# baseline (speedup 1.0000x reference)
.LBB0_923:
	s_barrier
	s_lshl_b32 s1, s18, 8
	v_readfirstlane_b32 s7, v0
	s_ashr_i32 s2, s7, 6
	s_mov_b32 s87, s2
	s_and_b32 s0, s2, 3
	s_lshl_b32 s3, s0, 5
	s_or_b32 s1, s3, s1
	v_lshrrev_b32_e32 v130, 2, v0
	v_and_or_b32 v130, v130, 12, s1
	v_mov_b32_e32 v147, 0
	v_lshlrev_b32_e32 v146, 2, v130
	v_lshl_add_u64 v[130:131], s[82:83], 0, v[146:147]
	s_mov_b64 s[4:5], 0xb40000
	v_lshl_add_u64 v[142:143], v[130:131], 0, s[4:5]
	v_and_b32_e32 v167, 15, v0
	s_ashr_i32 s4, s7, 8
	v_lshl_or_b32 v166, s4, 6, v167
	s_lshl_b32 s3, s6, 8
	v_add_u32_e32 v148, s3, v166
	v_readlane_b32 s36, v254, 8
	v_ashrrev_i32_e32 v149, 31, v148
	v_readlane_b32 s37, v254, 9
	s_mov_b32 s1, 0xb40000
	v_lshlrev_b64 v[134:135], 12, v[148:149]
	s_mov_b64 s[12:13], s[36:37]
	v_add_co_u32_e32 v130, vcc, s1, v130
	v_lshl_add_u64 v[134:135], s[12:13], 0, v[134:135]
	s_nop 0
	v_addc_co_u32_e32 v131, vcc, 0, v131, vcc
	v_lshl_add_u64 v[144:145], v[134:135], 0, v[146:147]
	global_load_dwordx4 v[130:133], v[130:131], off
	s_nop 0
	global_load_dwordx4 v[152:155], v[144:145], off nt
	global_load_dwordx4 v[156:159], v[144:145], off offset:64 nt
	global_load_dwordx4 v[138:141], v[142:143], off offset:64
	global_load_dwordx4 v[134:137], v[142:143], off offset:512
	global_load_dwordx4 v[160:163], v[144:145], off offset:512 nt
	global_load_dwordx4 v[168:171], v[144:145], off offset:576 nt
	s_nop 0
	global_load_dwordx4 v[142:145], v[142:143], off offset:576
	v_or_b32_e32 v150, 16, v148
	v_ashrrev_i32_e32 v151, 31, v150
	v_lshlrev_b64 v[172:173], 12, v[150:151]
	v_lshl_add_u64 v[172:173], s[12:13], 0, v[172:173]
	v_lshl_add_u64 v[172:173], v[172:173], 0, v[146:147]
	v_mbcnt_hi_u32_b32 v198, -1, v1
	v_xor_b32_e32 v1, 16, v198
	s_lshl_b32 s0, s0, 3
	s_add_i32 s5, s0, 0
	v_readlane_b32 s38, v254, 10
	v_readlane_b32 s39, v254, 11
	v_readlane_b32 s40, v254, 12
	v_readlane_b32 s41, v254, 13
	v_readlane_b32 s42, v254, 14
	v_readlane_b32 s43, v254, 15
	v_readlane_b32 s44, v254, 16
	v_readlane_b32 s45, v254, 17
	v_readlane_b32 s46, v254, 18
	v_readlane_b32 s47, v254, 19
	v_readlane_b32 s48, v254, 20
	v_readlane_b32 s49, v254, 21
	v_readlane_b32 s50, v254, 22
	v_readlane_b32 s51, v254, 23
	s_waitcnt vmcnt(0)
	v_pk_fma_f32 v[40:41], v[40:41], v[140:141], v[158:159]
	v_pk_fma_f32 v[38:39], v[38:39], v[138:139], v[156:157]
	v_pk_fma_f32 v[16:17], v[16:17], v[136:137], v[162:163]
	v_pk_fma_f32 v[68:69], v[68:69], v[132:133], v[154:155]
	v_pk_fma_f32 v[66:67], v[66:67], v[130:131], v[152:153]
	v_pk_fma_f32 v[14:15], v[14:15], v[134:135], v[160:161]
	v_pk_fma_f32 v[4:5], v[4:5], v[144:145], v[170:171]
	v_pk_fma_f32 v[2:3], v[2:3], v[142:143], v[168:169]
	v_or_b32_e32 v152, 32, v148
	global_load_dwordx4 v[154:157], v[172:173], off nt
	global_load_dwordx4 v[158:161], v[172:173], off offset:64 nt
	global_load_dwordx4 v[168:171], v[172:173], off offset:512 nt
	s_nop 0
	global_load_dwordx4 v[172:175], v[172:173], off offset:576 nt
	v_ashrrev_i32_e32 v153, 31, v152
	v_lshlrev_b64 v[162:163], 12, v[152:153]
	v_lshl_add_u64 v[162:163], s[12:13], 0, v[162:163]
	v_lshl_add_u64 v[176:177], v[162:163], 0, v[146:147]
	v_mov_b32_e32 v188, v67
	v_mov_b32_e32 v189, v68
	v_mov_b32_e32 v190, v66
	v_mov_b32_e32 v191, v69
	v_mov_b32_e32 v192, v39
	v_mov_b32_e32 v193, v40
	v_pk_add_f32 v[188:189], v[188:189], v[190:191]
	v_add_f32_e32 v195, v16, v17
	v_mov_b32_e32 v194, v3
	v_mov_b32_e32 v196, v5
	s_waitcnt vmcnt(3)
	v_pk_fma_f32 v[80:81], v[80:81], v[132:133], v[156:157]
	v_pk_fma_f32 v[78:79], v[78:79], v[130:131], v[154:155]
	s_waitcnt vmcnt(2)
	v_pk_fma_f32 v[48:49], v[48:49], v[140:141], v[160:161]
	v_pk_fma_f32 v[46:47], v[46:47], v[138:139], v[158:159]
	s_waitcnt vmcnt(1)
	v_pk_fma_f32 v[24:25], v[24:25], v[136:137], v[170:171]
	v_pk_fma_f32 v[22:23], v[22:23], v[134:135], v[168:169]
	s_waitcnt vmcnt(0)
	v_pk_fma_f32 v[8:9], v[8:9], v[144:145], v[174:175]
	v_pk_fma_f32 v[6:7], v[6:7], v[142:143], v[172:173]
	v_or_b32_e32 v154, 48, v148
	global_load_dwordx4 v[156:159], v[176:177], off nt
	global_load_dwordx4 v[160:163], v[176:177], off offset:64 nt
	global_load_dwordx4 v[168:171], v[176:177], off offset:512 nt
	global_load_dwordx4 v[172:175], v[176:177], off offset:576 nt
	v_ashrrev_i32_e32 v155, 31, v154
	v_lshlrev_b64 v[176:177], 12, v[154:155]
	v_lshl_add_u64 v[176:177], s[12:13], 0, v[176:177]
	v_lshl_add_u64 v[176:177], v[176:177], 0, v[146:147]
	s_waitcnt vmcnt(3)
	v_pk_fma_f32 v[92:93], v[92:93], v[132:133], v[158:159]
	v_pk_fma_f32 v[90:91], v[90:91], v[130:131], v[156:157]
	s_waitcnt vmcnt(2)
	v_pk_fma_f32 v[60:61], v[60:61], v[140:141], v[162:163]
	v_pk_fma_f32 v[58:59], v[58:59], v[138:139], v[160:161]
	s_waitcnt vmcnt(1)
	v_pk_fma_f32 v[32:33], v[32:33], v[136:137], v[170:171]
	v_pk_fma_f32 v[30:31], v[30:31], v[134:135], v[168:169]
	s_waitcnt vmcnt(0)
	v_pk_fma_f32 v[12:13], v[12:13], v[144:145], v[174:175]
	v_pk_fma_f32 v[10:11], v[10:11], v[142:143], v[172:173]
	v_add_u32_e32 v156, 0x80, v148
	global_load_dwordx4 v[158:161], v[176:177], off nt
	global_load_dwordx4 v[168:171], v[176:177], off offset:64 nt
	global_load_dwordx4 v[172:175], v[176:177], off offset:512 nt
	s_nop 0
	global_load_dwordx4 v[176:179], v[176:177], off offset:576 nt
	v_ashrrev_i32_e32 v157, 31, v156
	v_lshlrev_b64 v[162:163], 12, v[156:157]
	v_lshl_add_u64 v[162:163], s[12:13], 0, v[162:163]
	v_lshl_add_u64 v[180:181], v[162:163], 0, v[146:147]
	s_waitcnt vmcnt(3)
	v_pk_fma_f32 v[104:105], v[104:105], v[132:133], v[160:161]
	v_pk_fma_f32 v[102:103], v[102:103], v[130:131], v[158:159]
	s_waitcnt vmcnt(2)
	v_pk_fma_f32 v[72:73], v[72:73], v[140:141], v[170:171]
	v_pk_fma_f32 v[70:71], v[70:71], v[138:139], v[168:169]
	s_waitcnt vmcnt(1)
	v_pk_fma_f32 v[44:45], v[44:45], v[136:137], v[174:175]
	v_pk_fma_f32 v[42:43], v[42:43], v[134:135], v[172:173]
	s_waitcnt vmcnt(0)
	v_pk_fma_f32 v[20:21], v[20:21], v[144:145], v[178:179]
	v_pk_fma_f32 v[18:19], v[18:19], v[142:143], v[176:177]
	v_add_u32_e32 v158, 0x90, v148
	global_load_dwordx4 v[160:163], v[180:181], off nt
	global_load_dwordx4 v[168:171], v[180:181], off offset:64 nt
	global_load_dwordx4 v[172:175], v[180:181], off offset:512 nt
	global_load_dwordx4 v[176:179], v[180:181], off offset:576 nt
	v_ashrrev_i32_e32 v159, 31, v158
	v_lshlrev_b64 v[180:181], 12, v[158:159]
	v_lshl_add_u64 v[180:181], s[12:13], 0, v[180:181]
	v_lshl_add_u64 v[180:181], v[180:181], 0, v[146:147]
	s_waitcnt vmcnt(3)
	v_pk_fma_f32 v[108:109], v[108:109], v[132:133], v[162:163]
	v_pk_fma_f32 v[106:107], v[106:107], v[130:131], v[160:161]
	s_waitcnt vmcnt(2)
	v_pk_fma_f32 v[84:85], v[84:85], v[140:141], v[170:171]
	v_pk_fma_f32 v[82:83], v[82:83], v[138:139], v[168:169]
	s_waitcnt vmcnt(1)
	v_pk_fma_f32 v[52:53], v[52:53], v[136:137], v[174:175]
	v_pk_fma_f32 v[50:51], v[50:51], v[134:135], v[172:173]
	s_waitcnt vmcnt(0)
	v_pk_fma_f32 v[28:29], v[28:29], v[144:145], v[178:179]
	v_pk_fma_f32 v[26:27], v[26:27], v[142:143], v[176:177]
	v_add_u32_e32 v160, 0xa0, v148
	global_load_dwordx4 v[168:171], v[180:181], off nt
	global_load_dwordx4 v[172:175], v[180:181], off offset:64 nt
	global_load_dwordx4 v[176:179], v[180:181], off offset:512 nt
	s_nop 0
	global_load_dwordx4 v[180:183], v[180:181], off offset:576 nt
	v_ashrrev_i32_e32 v161, 31, v160
	v_lshlrev_b64 v[162:163], 12, v[160:161]
	v_lshl_add_u64 v[162:163], s[12:13], 0, v[162:163]
	v_lshl_add_u64 v[162:163], v[162:163], 0, v[146:147]
	s_waitcnt vmcnt(3)
	v_pk_fma_f32 v[120:121], v[120:121], v[132:133], v[170:171]
	v_pk_fma_f32 v[118:119], v[118:119], v[130:131], v[168:169]
	s_waitcnt vmcnt(2)
	v_pk_fma_f32 v[96:97], v[96:97], v[140:141], v[174:175]
	v_pk_fma_f32 v[94:95], v[94:95], v[138:139], v[172:173]
	s_waitcnt vmcnt(1)
	v_pk_fma_f32 v[64:65], v[64:65], v[136:137], v[178:179]
	v_pk_fma_f32 v[62:63], v[62:63], v[134:135], v[176:177]
	s_waitcnt vmcnt(0)
	v_pk_fma_f32 v[36:37], v[36:37], v[144:145], v[182:183]
	v_pk_fma_f32 v[34:35], v[34:35], v[142:143], v[180:181]
	s_nop 0
	global_load_dwordx4 v[168:171], v[162:163], off nt
	global_load_dwordx4 v[172:175], v[162:163], off offset:64 nt
	global_load_dwordx4 v[176:179], v[162:163], off offset:512 nt
	global_load_dwordx4 v[180:183], v[162:163], off offset:576 nt
	v_and_b32_e32 v162, 64, v198
	v_add_u32_e32 v199, 64, v162
	v_add_u32_e32 v162, 0xb0, v148
	v_ashrrev_i32_e32 v163, 31, v162
	v_lshlrev_b64 v[184:185], 12, v[162:163]
	v_lshl_add_u64 v[184:185], s[12:13], 0, v[184:185]
	v_lshl_add_u64 v[184:185], v[184:185], 0, v[146:147]
	v_add_f32_e32 v147, v188, v189
	v_add_f32_e32 v197, 0, v147
	v_cmp_lt_i32_e32 vcc, v1, v199
	s_waitcnt vmcnt(3)
	v_pk_fma_f32 v[128:129], v[128:129], v[132:133], v[170:171]
	v_pk_fma_f32 v[126:127], v[126:127], v[130:131], v[168:169]
	s_waitcnt vmcnt(2)
	v_pk_fma_f32 v[112:113], v[112:113], v[140:141], v[174:175]
	v_pk_fma_f32 v[110:111], v[110:111], v[138:139], v[172:173]
	s_waitcnt vmcnt(1)
	v_pk_fma_f32 v[88:89], v[88:89], v[136:137], v[178:179]
	v_pk_fma_f32 v[86:87], v[86:87], v[134:135], v[176:177]
	s_waitcnt vmcnt(0)
	v_pk_fma_f32 v[56:57], v[56:57], v[144:145], v[182:183]
	v_pk_fma_f32 v[54:55], v[54:55], v[142:143], v[180:181]
	v_mov_b32_e32 v168, v38
	global_load_dwordx4 v[172:175], v[184:185], off nt
	global_load_dwordx4 v[176:179], v[184:185], off offset:64 nt
	global_load_dwordx4 v[180:183], v[184:185], off offset:512 nt
	v_mov_b32_e32 v169, v41
	global_load_dwordx4 v[184:187], v[184:185], off offset:576 nt
	v_pk_add_f32 v[168:169], v[192:193], v[168:169]
	v_add_f32_e32 v171, v14, v15
	v_pk_add_f32 v[168:169], v[168:169], v[168:169] op_sel_hi:[0,1]
	v_mov_b32_e32 v170, v2
	v_mov_b32_e32 v168, v4
	v_pk_add_f32 v[170:171], v[170:171], v[194:195]
	v_pk_add_f32 v[168:169], v[168:169], v[196:197]
	v_cndmask_b32_e32 v1, v198, v1, vcc
	v_pk_add_f32 v[168:169], v[170:171], v[168:169]
	v_lshlrev_b32_e32 v1, 2, v1
	v_add_f32_e32 v147, v168, v169
	ds_bpermute_b32 v169, v1, v147
	v_xor_b32_e32 v168, 32, v198
	v_cmp_lt_i32_e32 vcc, v168, v199
	s_waitcnt lgkmcnt(0)
	v_add_f32_e32 v147, v147, v169
	v_cndmask_b32_e32 v168, v198, v168, vcc
	v_lshlrev_b32_e32 v168, 2, v168
	ds_bpermute_b32 v169, v168, v147
	s_waitcnt lgkmcnt(0)
	v_add_f32_e32 v169, v147, v169
	v_fmamk_f32 v170, v169, 0xbc800000, v69
	v_fmamk_f32 v188, v169, 0xbc800000, v67
	v_fmamk_f32 v190, v169, 0xbc800000, v41
	v_fmamk_f32 v192, v169, 0xbc800000, v39
	v_fmamk_f32 v147, v169, 0xbc800000, v68
	v_fmamk_f32 v171, v169, 0xbc800000, v66
	v_fmamk_f32 v189, v169, 0xbc800000, v40
	v_fmamk_f32 v191, v169, 0xbc800000, v38
	v_fmamk_f32 v194, v169, 0xbc800000, v17
	v_fmamk_f32 v196, v169, 0xbc800000, v15
	v_mul_f32_e32 v188, v188, v188
	v_mul_f32_e32 v170, v170, v170
	v_mul_f32_e32 v192, v192, v192
	v_mul_f32_e32 v190, v190, v190
	v_fmamk_f32 v193, v169, 0xbc800000, v16
	v_fmamk_f32 v195, v169, 0xbc800000, v14
	v_fmamk_f32 v198, v169, 0xbc800000, v5
	v_fmamk_f32 v200, v169, 0xbc800000, v3
	v_mul_f32_e32 v196, v196, v196
	v_mul_f32_e32 v194, v194, v194
	v_fmac_f32_e32 v188, v171, v171
	v_fmac_f32_e32 v170, v147, v147
	v_fmac_f32_e32 v192, v191, v191
	v_fmac_f32_e32 v190, v189, v189
	v_fmamk_f32 v197, v169, 0xbc800000, v4
	v_fmamk_f32 v199, v169, 0xbc800000, v2
	v_mul_f32_e32 v200, v200, v200
	v_mul_f32_e32 v198, v198, v198
	v_fmac_f32_e32 v196, v195, v195
	v_fmac_f32_e32 v194, v193, v193
	v_add_f32_e32 v147, v188, v170
	v_add_f32_e32 v170, v192, v190
	v_fmac_f32_e32 v200, v199, v199
	v_fmac_f32_e32 v198, v197, v197
	v_add_f32_e32 v171, v196, v194
	v_add_f32_e32 v147, v147, v170
	v_add_f32_e32 v188, v200, v198
	v_add_f32_e32 v147, v171, v147
	v_add_f32_e32 v170, v188, v147
	ds_bpermute_b32 v171, v1, v170
	v_and_b32_e32 v147, 63, v0
	v_cmp_gt_u32_e32 vcc, 16, v147
	s_waitcnt lgkmcnt(0)
	v_add_f32_e32 v170, v170, v171
	ds_bpermute_b32 v171, v168, v170
	s_waitcnt vmcnt(3)
	v_pk_fma_f32 v[124:125], v[124:125], v[132:133], v[174:175]
	v_pk_fma_f32 v[122:123], v[122:123], v[130:131], v[172:173]
	s_waitcnt vmcnt(2)
	v_pk_fma_f32 v[116:117], v[116:117], v[140:141], v[178:179]
	v_pk_fma_f32 v[114:115], v[114:115], v[138:139], v[176:177]
	s_waitcnt vmcnt(1)
	v_pk_fma_f32 v[100:101], v[100:101], v[136:137], v[182:183]
	v_pk_fma_f32 v[98:99], v[98:99], v[134:135], v[180:181]
	s_waitcnt vmcnt(0)
	v_pk_fma_f32 v[76:77], v[76:77], v[144:145], v[186:187]
	v_pk_fma_f32 v[74:75], v[74:75], v[142:143], v[184:185]
	s_nop 0
	s_and_saveexec_b64 s[0:1], vcc
	s_cbranch_execz .LBB0_925
	s_lshl_b32 s10, s4, 11
	s_add_i32 s10, s5, s10
	v_mul_f32_e32 v130, 0x3c800000, v169
	v_lshl_add_u32 v132, v167, 5, s10
	s_waitcnt lgkmcnt(0)
	v_add_f32_e32 v131, v170, v171
	ds_write_b64 v132, v[130:131]
